# NA stage loop: remaining s_nop removed by re-ordering (late rpb reads behind address VALU, converts before the V wait, PV MFMA order)
# speedup vs baseline: 1.0027x; 1.0027x over previous
.LBB0_202:
	v_add_u32_e32 v0, v93, v88
	v_add_u32_e32 v72, v93, v87
	ds_read_b128 v[50:53], v0 offset:32768
	ds_read_b128 v[54:57], v72 offset:32768
	ds_read_b128 v[156:159], v0 offset:40960
	ds_read_b128 v[160:163], v72 offset:40960
	v_add_u32_e32 v67, s98, v117
	v_add_u32_e32 v62, s99, v117
	s_waitcnt lgkmcnt(2)
	v_mfma_f32_16x16x32_bf16 v[58:61], v[46:49], v[50:53], 0
	v_add_u32_e32 v63, s30, v117
	v_add_u32_e32 v68, s4, v117
	s_add_i32 s10, s81, s8
	v_add_u32_e32 v66, s97, v117
	ds_read2_b32 v[64:65], v68 offset1:1
	ds_read2_b32 v[70:71], v68 offset0:2 offset1:3
	ds_read_b32 v68, v63
	ds_read_b32 v69, v62
	v_mfma_f32_16x16x32_bf16 v[60:63], v[42:45], v[54:57], v[58:61]
	v_add_u32_e32 v172, v128, v116
	v_add_u32_e32 v173, 0x10364, v172
	v_add_u32_e32 v174, 0x1036c, v172
	v_add_u32_e32 v175, 0x103a4, v172
	v_add_u32_e32 v172, 0x103ac, v172
	ds_read_b32 v58, v67
	ds_read_b32 v59, v66
	ds_read2_b32 v[164:165], v173 offset1:1
	ds_read2_b32 v[166:167], v174 offset1:1
	ds_read2_b32 v[168:169], v175 offset1:1
	ds_read2_b32 v[170:171], v172 offset1:1
	s_cmp_ge_u32 s10, s80
	s_cselect_b64 s[0:1], -1, 0
	v_mfma_f32_16x16x32_bf16 v[50:53], v[6:9], v[50:53], 0
	s_cmp_lt_u32 s10, s89
	s_cselect_b64 s[8:9], -1, 0
	s_and_b64 s[0:1], s[0:1], s[8:9]
	s_waitcnt lgkmcnt(4)
	v_mfma_f32_16x16x32_bf16 v[50:53], v[2:5], v[54:57], v[50:53]
	v_add_u32_e32 v172, s6, v107
	v_add3_u32 v154, v172, v82, v83
	v_add_u32_e32 v172, s6, v106
	v_add3_u32 v155, v172, v82, v83
	ds_read_b64 v[176:177], v154 offset:8192
	ds_read_b64 v[178:179], v155 offset:8192
	ds_read_b64 v[180:181], v154 offset:10240
	ds_read_b64 v[182:183], v155 offset:10240
	ds_read_b64 v[236:237], v154 offset:12288
	ds_read_b64 v[238:239], v155 offset:12288
	ds_read_b64 v[244:245], v154 offset:14336
	ds_read_b64 v[246:247], v155 offset:14336
	v_mfma_f32_16x16x32_bf16 v[46:49], v[46:49], v[156:159], 0
	v_mfma_f32_16x16x32_bf16 v[6:9], v[6:9], v[156:159], 0
	v_mfma_f32_16x16x32_bf16 v[42:45], v[42:45], v[160:163], v[46:49]
	v_mfma_f32_16x16x32_bf16 v[2:5], v[2:5], v[160:163], v[6:9]
	v_add_f32_e32 v54, v59, v60
	s_and_b64 vcc, s[0:1], s[40:41]
	v_cndmask_b32_e32 v60, v196, v54, vcc
	v_add_f32_e32 v54, v58, v61
	s_and_b64 vcc, s[0:1], s[42:43]
	v_cndmask_b32_e32 v61, v196, v54, vcc
	v_add_f32_e32 v54, v69, v62
	s_and_b64 vcc, s[0:1], s[44:45]
	v_cndmask_b32_e32 v66, v196, v54, vcc
	v_add_f32_e32 v54, v68, v63
	s_and_b64 vcc, s[0:1], s[46:47]
	v_cndmask_b32_e32 v67, v196, v54, vcc
	v_add_f32_e32 v50, v64, v50
	s_and_b64 vcc, s[0:1], s[48:49]
	v_cndmask_b32_e32 v68, v196, v50, vcc
	v_add_f32_e32 v50, v65, v51
	s_and_b64 vcc, s[0:1], s[50:51]
	v_cndmask_b32_e32 v69, v196, v50, vcc
	v_add_f32_e32 v50, v70, v52
	s_and_b64 vcc, s[0:1], s[52:53]
	v_cndmask_b32_e32 v76, v196, v50, vcc
	v_add_f32_e32 v50, v71, v53
	s_and_b64 vcc, s[0:1], s[54:55]
	v_cndmask_b32_e32 v77, v196, v50, vcc
	s_cmp_ge_u32 s10, s56
	s_cselect_b64 s[0:1], -1, 0
	s_cmp_lt_u32 s10, s57
	s_cselect_b64 s[8:9], -1, 0
	s_and_b64 s[0:1], s[0:1], s[8:9]
	s_and_b64 vcc, s[0:1], s[40:41]
	s_waitcnt lgkmcnt(8)
	v_add_f32_e32 v6, v164, v42
	v_cndmask_b32_e32 v130, v196, v6, vcc
	v_add_f32_e32 v6, v165, v43
	s_and_b64 vcc, s[0:1], s[42:43]
	v_cndmask_b32_e32 v131, v196, v6, vcc
	v_add_f32_e32 v6, v166, v44
	s_and_b64 vcc, s[0:1], s[44:45]
	v_cndmask_b32_e32 v132, v196, v6, vcc
	v_add_f32_e32 v6, v167, v45
	s_and_b64 vcc, s[0:1], s[46:47]
	v_cndmask_b32_e32 v133, v196, v6, vcc
	v_add_f32_e32 v2, v168, v2
	s_and_b64 vcc, s[0:1], s[48:49]
	v_cndmask_b32_e32 v136, v196, v2, vcc
	v_add_f32_e32 v2, v169, v3
	s_and_b64 vcc, s[0:1], s[50:51]
	v_cndmask_b32_e32 v137, v196, v2, vcc
	v_add_f32_e32 v0, v170, v4
	s_and_b64 vcc, s[0:1], s[52:53]
	v_cndmask_b32_e32 v138, v196, v0, vcc
	v_add_f32_e32 v0, v171, v5
	s_and_b64 vcc, s[0:1], s[54:55]
	v_max_f32_e32 v3, v76, v77
	v_cndmask_b32_e32 v139, v196, v0, vcc
	v_max_f32_e32 v0, v60, v61
	v_max_f32_e32 v2, v66, v67
	v_max3_f32 v3, v68, v69, v3
	v_max3_f32 v143, v0, v2, v3
	v_add_f32_e32 v0, 0x41000000, v75
	v_max_f32_e32 v3, v138, v139
	v_cmp_gt_f32_e32 vcc, v143, v0
	v_max_f32_e32 v0, v130, v131
	v_max_f32_e32 v2, v132, v133
	v_max3_f32 v3, v136, v137, v3
	v_max3_f32 v142, v0, v2, v3
	v_add_f32_e32 v0, 0x41000000, v74
	v_cmp_gt_f32_e64 s[0:1], v142, v0
	s_or_b64 vcc, vcc, s[0:1]
	v_mov_b32_e32 v140, v74
	v_mov_b32_e32 v141, v75
	v_mov_b64_e32 v[58:59], v[78:79]
	v_mov_b32_e32 v129, v74
	v_mov_b32_e32 v0, v75
	s_cbranch_vccz .LBB0_204
	ds_bpermute_b32 v0, v186, v143
	v_max_f32_e32 v2, v143, v143
	ds_bpermute_b32 v3, v186, v142
	v_max_f32_e32 v4, v142, v142
	s_waitcnt lgkmcnt(0)
	v_max_f32_e32 v0, v0, v0
	v_max_f32_e32 v0, v2, v0
	ds_bpermute_b32 v2, v187, v0
	s_waitcnt lgkmcnt(0)
	v_max3_f32 v141, v75, v0, v2
	v_max_f32_e32 v2, v3, v3
	v_max_f32_e32 v6, v4, v2
	ds_bpermute_b32 v7, v187, v6
	v_sub_f32_e32 v0, v75, v141
	v_exp_f32_e32 v0, v0
	s_waitcnt lgkmcnt(0)
	v_max3_f32 v140, v74, v6, v7
	v_sub_f32_e32 v6, v74, v140
	v_exp_f32_e32 v62, v6
	v_mov_b32_e32 v63, v0
	v_pk_mul_f32 v[40:41], v[40:41], v[0:1] op_sel_hi:[1,0]
	v_pk_mul_f32 v[38:39], v[38:39], v[0:1] op_sel_hi:[1,0]
	v_pk_mul_f32 v[36:37], v[36:37], v[0:1] op_sel_hi:[1,0]
	v_pk_mul_f32 v[34:35], v[34:35], v[0:1] op_sel_hi:[1,0]
	v_pk_mul_f32 v[24:25], v[24:25], v[0:1] op_sel_hi:[1,0]
	v_pk_mul_f32 v[22:23], v[22:23], v[0:1] op_sel_hi:[1,0]
	v_pk_mul_f32 v[16:17], v[16:17], v[0:1] op_sel_hi:[1,0]
	v_pk_mul_f32 v[14:15], v[14:15], v[0:1] op_sel_hi:[1,0]
	v_pk_mul_f32 v[58:59], v[78:79], v[62:63]
	v_pk_mul_f32 v[32:33], v[32:33], v[62:63] op_sel_hi:[1,0]
	v_pk_mul_f32 v[30:31], v[30:31], v[62:63] op_sel_hi:[1,0]
	v_pk_mul_f32 v[28:29], v[28:29], v[62:63] op_sel_hi:[1,0]
	v_pk_mul_f32 v[26:27], v[26:27], v[62:63] op_sel_hi:[1,0]
	v_pk_mul_f32 v[20:21], v[20:21], v[62:63] op_sel_hi:[1,0]
	v_pk_mul_f32 v[18:19], v[18:19], v[62:63] op_sel_hi:[1,0]
	v_pk_mul_f32 v[12:13], v[12:13], v[62:63] op_sel_hi:[1,0]
	v_pk_mul_f32 v[10:11], v[10:11], v[62:63] op_sel_hi:[1,0]
	v_mov_b32_e32 v129, v140
	v_mov_b32_e32 v0, v141

.LBB0_205:
	s_and_b64 vcc, exec, s[0:1]
	s_cbranch_vccz .LBB0_217
	v_add_u32_e32 v58, s6, v88
	v_add_u32_e32 v59, s6, v87
	ds_read_b128 v[6:9], v58
	ds_read_b128 v[50:53], v58 offset:2048
	ds_read_b128 v[46:49], v59
	ds_read_b128 v[54:57], v59 offset:2048
	s_cmp_lt_i32 s7, 0
	s_cbranch_scc1 .LBB0_212
	s_cmp_gt_i32 s7, s82
	s_mov_b64 s[0:1], -1
	s_cbranch_scc1 .LBB0_209
	s_add_i32 s0, s7, s81
	s_lshl_b32 s0, s0, 6
	s_add_i32 s8, s0, 0x100
	s_mov_b64 s[0:1], 0

.LBB0_212:
	v_add_u32_e32 v60, v93, v88
	ds_read_b128 v[2:5], v60 offset:32768
	v_add_u32_e32 v0, v93, v87
	ds_read_b128 v[62:65], v0 offset:32768
	ds_read_b128 v[156:159], v60 offset:40960
	ds_read_b128 v[160:163], v0 offset:40960
	s_waitcnt lgkmcnt(2)
	v_mfma_f32_16x16x32_bf16 v[42:45], v[6:9], v[2:5], 0
	v_mfma_f32_16x16x32_bf16 v[2:5], v[50:53], v[2:5], 0
	v_mfma_f32_16x16x32_bf16 v[42:45], v[46:49], v[62:65], v[42:45]
	v_mfma_f32_16x16x32_bf16 v[2:5], v[54:57], v[62:65], v[2:5]
	v_add_u32_e32 v172, s6, v86
	v_add3_u32 v173, v172, v82, v83
	v_add_u32_e32 v172, s6, v85
	v_add3_u32 v174, v172, v82, v83
	ds_read_b64 v[176:177], v173 offset:8192
	ds_read_b64 v[178:179], v174 offset:8192
	ds_read_b64 v[180:181], v173 offset:10240
	ds_read_b64 v[182:183], v174 offset:10240
	ds_read_b64 v[236:237], v173 offset:12288
	ds_read_b64 v[238:239], v174 offset:12288
	ds_read_b64 v[244:245], v173 offset:14336
	ds_read_b64 v[246:247], v174 offset:14336
	s_waitcnt lgkmcnt(8)
	v_mfma_f32_16x16x32_bf16 v[6:9], v[6:9], v[156:159], 0
	v_mfma_f32_16x16x32_bf16 v[46:49], v[46:49], v[160:163], v[6:9]
	v_mfma_f32_16x16x32_bf16 v[6:9], v[50:53], v[156:159], 0
	v_max_f32_e32 v50, v43, v43
	v_max_f32_e32 v51, v42, v42
	v_max_f32_e32 v50, v51, v50
	v_max_f32_e32 v51, v45, v45
	v_max_f32_e32 v52, v44, v44
	v_max_f32_e32 v51, v52, v51
	v_max_f32_e32 v52, v5, v5
	v_max_f32_e32 v53, v4, v4
	v_mfma_f32_16x16x32_bf16 v[6:9], v[54:57], v[160:163], v[6:9]
	v_max_f32_e32 v52, v53, v52
	v_max3_f32 v52, v2, v3, v52
	v_max3_f32 v51, v50, v51, v52
	v_max_f32_e32 v50, v47, v47
	v_max_f32_e32 v54, v46, v46
	v_max_f32_e32 v50, v54, v50
	v_max_f32_e32 v54, v49, v49
	v_max_f32_e32 v55, v48, v48
	v_max_f32_e32 v54, v55, v54
	v_max_f32_e32 v55, v9, v9
	v_max_f32_e32 v56, v8, v8
	v_max_f32_e32 v55, v56, v55
	v_max3_f32 v55, v6, v7, v55
	v_pk_add_f32 v[52:53], v[74:75], s[12:13] op_sel_hi:[1,0]
	v_max3_f32 v50, v50, v54, v55
	v_cmp_gt_f32_e32 vcc, v51, v53
	v_cmp_gt_f32_e64 s[0:1], v50, v52
	s_or_b64 vcc, vcc, s[0:1]
	s_cbranch_vccz .LBB0_214
	ds_bpermute_b32 v52, v186, v51
	v_max_f32_e32 v51, v51, v51
	s_waitcnt lgkmcnt(0)
	v_max_f32_e32 v52, v52, v52
	v_max_f32_e32 v51, v51, v52
	ds_bpermute_b32 v52, v187, v51
	s_waitcnt lgkmcnt(0)
	v_max3_f32 v51, v75, v51, v52
	v_sub_f32_e32 v52, v75, v51
	v_exp_f32_e32 v52, v52
	v_mov_b32_e32 v75, v51
	v_pk_mul_f32 v[40:41], v[40:41], v[52:53] op_sel_hi:[1,0]
	v_pk_mul_f32 v[38:39], v[38:39], v[52:53] op_sel_hi:[1,0]
	v_pk_mul_f32 v[36:37], v[36:37], v[52:53] op_sel_hi:[1,0]
	v_pk_mul_f32 v[34:35], v[34:35], v[52:53] op_sel_hi:[1,0]
	v_pk_mul_f32 v[24:25], v[24:25], v[52:53] op_sel_hi:[1,0]
	v_pk_mul_f32 v[22:23], v[22:23], v[52:53] op_sel_hi:[1,0]
	v_pk_mul_f32 v[16:17], v[16:17], v[52:53] op_sel_hi:[1,0]
	v_pk_mul_f32 v[14:15], v[14:15], v[52:53] op_sel_hi:[1,0]
	ds_bpermute_b32 v53, v186, v50
	v_max_f32_e32 v50, v50, v50
	v_mov_b32_e32 v55, v52
	s_waitcnt lgkmcnt(0)
	v_max_f32_e32 v53, v53, v53
	v_max_f32_e32 v50, v50, v53
	ds_bpermute_b32 v53, v187, v50
	s_waitcnt lgkmcnt(0)
	v_max3_f32 v50, v74, v50, v53
	v_sub_f32_e32 v53, v74, v50
	v_exp_f32_e32 v54, v53
	v_pk_add_f32 v[52:53], v[50:51], s[12:13] op_sel_hi:[1,0]
	v_mov_b32_e32 v74, v50
	v_pk_mul_f32 v[78:79], v[78:79], v[54:55]
	v_pk_mul_f32 v[32:33], v[32:33], v[54:55] op_sel_hi:[1,0]
	v_pk_mul_f32 v[30:31], v[30:31], v[54:55] op_sel_hi:[1,0]
	v_pk_mul_f32 v[28:29], v[28:29], v[54:55] op_sel_hi:[1,0]
	v_pk_mul_f32 v[26:27], v[26:27], v[54:55] op_sel_hi:[1,0]
	v_pk_mul_f32 v[20:21], v[20:21], v[54:55] op_sel_hi:[1,0]
	v_pk_mul_f32 v[18:19], v[18:19], v[54:55] op_sel_hi:[1,0]
	v_pk_mul_f32 v[12:13], v[12:13], v[54:55] op_sel_hi:[1,0]
	v_pk_mul_f32 v[10:11], v[10:11], v[54:55] op_sel_hi:[1,0]
.LBB0_214:
	v_sub_f32_e32 v2, v2, v75
	v_exp_f32_e32 v67, v2
	v_sub_f32_e32 v2, v3, v75
	v_exp_f32_e32 v3, v2
	v_sub_f32_e32 v2, v4, v75
	v_exp_f32_e32 v69, v2
	v_sub_f32_e32 v2, v5, v75
	v_sub_f32_e32 v42, v42, v75
	v_exp_f32_e32 v5, v2
	v_sub_f32_e32 v2, v46, v74
	v_exp_f32_e32 v55, v42
	v_sub_f32_e32 v42, v43, v75
	v_exp_f32_e32 v54, v2
	v_sub_f32_e32 v2, v47, v74
	v_exp_f32_e32 v57, v42
	v_sub_f32_e32 v42, v44, v75
	v_exp_f32_e32 v56, v2
	v_sub_f32_e32 v2, v48, v74
	v_exp_f32_e32 v63, v42
	v_sub_f32_e32 v42, v45, v75
	v_exp_f32_e32 v62, v2
	v_sub_f32_e32 v2, v49, v74
	v_exp_f32_e32 v65, v42
	v_exp_f32_e32 v64, v2
	v_sub_f32_e32 v2, v6, v74
	v_pk_add_f32 v[46:47], v[54:55], 0 op_sel_hi:[1,0]
	v_exp_f32_e32 v66, v2
	v_sub_f32_e32 v2, v7, v74
	v_pk_add_f32 v[46:47], v[56:57], v[46:47]
	v_exp_f32_e32 v2, v2
	v_sub_f32_e32 v4, v8, v74
	v_exp_f32_e32 v68, v4
	v_sub_f32_e32 v4, v9, v74
	v_pk_add_f32 v[6:7], v[62:63], v[46:47]
	v_exp_f32_e32 v4, v4
	v_pk_add_f32 v[6:7], v[64:65], v[6:7]
	v_pk_add_f32 v[6:7], v[66:67], v[6:7]
	v_pk_add_f32 v[6:7], v[2:3], v[6:7]
	v_pk_add_f32 v[6:7], v[68:69], v[6:7]
	v_cvt_pk_bf16_f32 v44, v67, v3
	v_cvt_pk_bf16_f32 v45, v69, v5
	v_pk_add_f32 v[6:7], v[4:5], v[6:7]
	v_cvt_pk_bf16_f32 v8, v66, v2
	v_cvt_pk_bf16_f32 v9, v68, v4
	v_cvt_pk_bf16_f32 v42, v55, v57
	v_pk_add_f32 v[50:51], v[78:79], v[6:7]
	v_cvt_pk_bf16_f32 v6, v54, v56
	v_cvt_pk_bf16_f32 v43, v63, v65
	v_cvt_pk_bf16_f32 v7, v62, v64
	s_waitcnt lgkmcnt(0)
	v_mfma_f32_16x16x32_bf16 v[38:41], v[176:179], v[42:45], v[38:41]
	v_mfma_f32_16x16x32_bf16 v[30:33], v[176:179], v[6:9], v[30:33]
	v_mfma_f32_16x16x32_bf16 v[34:37], v[180:183], v[42:45], v[34:37]
	v_mfma_f32_16x16x32_bf16 v[26:29], v[180:183], v[6:9], v[26:29]
	v_mfma_f32_16x16x32_bf16 v[22:25], v[236:239], v[42:45], v[22:25]
	v_mfma_f32_16x16x32_bf16 v[2:5], v[236:239], v[6:9], v[18:21]
	v_mfma_f32_16x16x32_bf16 v[14:17], v[244:247], v[42:45], v[14:17]
	v_mfma_f32_16x16x32_bf16 v[6:9], v[244:247], v[6:9], v[10:13]
	ds_read_b128 v[42:45], v58 offset:4096
	ds_read_b128 v[46:49], v59 offset:4096
	ds_read_b128 v[54:57], v58 offset:6144
	ds_read_b128 v[62:65], v59 offset:6144
	ds_read_b128 v[10:13], v60 offset:32768
	ds_read_b128 v[66:69], v0 offset:32768
	ds_read_b128 v[156:159], v60 offset:40960
	ds_read_b128 v[160:163], v0 offset:40960
	s_waitcnt lgkmcnt(2)
	v_mfma_f32_16x16x32_bf16 v[18:21], v[42:45], v[10:13], 0
	v_mfma_f32_16x16x32_bf16 v[10:13], v[54:57], v[10:13], 0
	v_mfma_f32_16x16x32_bf16 v[18:21], v[46:49], v[66:69], v[18:21]
	v_mfma_f32_16x16x32_bf16 v[10:13], v[62:65], v[66:69], v[10:13]
	v_add_u32_e32 v172, s6, v84
	v_add3_u32 v173, v172, v82, v83
	v_add_u32_e32 v172, s6, v81
	v_add3_u32 v174, v172, v82, v83
	ds_read_b64 v[176:177], v173 offset:8192
	ds_read_b64 v[178:179], v174 offset:8192
	ds_read_b64 v[180:181], v173 offset:10240
	ds_read_b64 v[182:183], v174 offset:10240
	ds_read_b64 v[236:237], v173 offset:12288
	ds_read_b64 v[238:239], v174 offset:12288
	ds_read_b64 v[244:245], v173 offset:14336
	ds_read_b64 v[246:247], v174 offset:14336
	v_max_f32_e32 v0, v19, v19
	s_waitcnt lgkmcnt(8)
	v_mfma_f32_16x16x32_bf16 v[42:45], v[42:45], v[156:159], 0
	v_mfma_f32_16x16x32_bf16 v[46:49], v[46:49], v[160:163], v[42:45]
	v_mfma_f32_16x16x32_bf16 v[42:45], v[54:57], v[156:159], 0
	v_max_f32_e32 v54, v18, v18
	v_max_f32_e32 v0, v54, v0
	v_max_f32_e32 v54, v21, v21
	v_max_f32_e32 v55, v20, v20
	v_max_f32_e32 v54, v55, v54
	v_max_f32_e32 v55, v13, v13
	v_max_f32_e32 v56, v12, v12
	v_max_f32_e32 v55, v56, v55
	v_mfma_f32_16x16x32_bf16 v[42:45], v[62:65], v[160:163], v[42:45]
	v_max3_f32 v55, v10, v11, v55
	v_max3_f32 v54, v0, v54, v55
	v_cmp_gt_f32_e32 vcc, v54, v53
	v_max_f32_e32 v0, v47, v47
	v_max_f32_e32 v53, v46, v46
	v_max_f32_e32 v0, v53, v0
	v_max_f32_e32 v53, v49, v49
	v_max_f32_e32 v55, v48, v48
	v_max_f32_e32 v53, v55, v53
	v_max_f32_e32 v55, v45, v45
	v_max_f32_e32 v56, v44, v44
	v_max_f32_e32 v55, v56, v55
	v_max3_f32 v55, v42, v43, v55
	v_max3_f32 v0, v0, v53, v55
	v_cmp_gt_f32_e64 s[0:1], v0, v52
	s_or_b64 vcc, vcc, s[0:1]
	s_cbranch_vccz .LBB0_216
	ds_bpermute_b32 v52, v186, v54
	v_max_f32_e32 v53, v54, v54
	ds_bpermute_b32 v54, v186, v0
	v_max_f32_e32 v0, v0, v0
	s_waitcnt lgkmcnt(0)
	v_max_f32_e32 v52, v52, v52
	v_max_f32_e32 v52, v53, v52
	v_max_f32_e32 v54, v54, v54
	ds_bpermute_b32 v53, v187, v52
	v_max_f32_e32 v0, v0, v54
	ds_bpermute_b32 v54, v187, v0
	s_waitcnt lgkmcnt(0)
	v_max3_f32 v53, v75, v52, v53
	v_sub_f32_e32 v52, v75, v53
	v_max3_f32 v0, v74, v0, v54
	v_exp_f32_e32 v52, v52
	v_sub_f32_e32 v54, v74, v0
	v_exp_f32_e32 v54, v54
	v_mov_b32_e32 v74, v0
	v_mov_b32_e32 v55, v52
	v_pk_mul_f32 v[40:41], v[40:41], v[52:53] op_sel_hi:[1,0]
	v_pk_mul_f32 v[38:39], v[38:39], v[52:53] op_sel_hi:[1,0]
	v_pk_mul_f32 v[36:37], v[36:37], v[52:53] op_sel_hi:[1,0]
	v_pk_mul_f32 v[34:35], v[34:35], v[52:53] op_sel_hi:[1,0]
	v_pk_mul_f32 v[24:25], v[24:25], v[52:53] op_sel_hi:[1,0]
	v_pk_mul_f32 v[22:23], v[22:23], v[52:53] op_sel_hi:[1,0]
	v_pk_mul_f32 v[16:17], v[16:17], v[52:53] op_sel_hi:[1,0]
	v_pk_mul_f32 v[14:15], v[14:15], v[52:53] op_sel_hi:[1,0]
	v_pk_mul_f32 v[50:51], v[50:51], v[54:55]
	v_pk_mul_f32 v[32:33], v[32:33], v[54:55] op_sel_hi:[1,0]
	v_pk_mul_f32 v[30:31], v[30:31], v[54:55] op_sel_hi:[1,0]
	v_pk_mul_f32 v[28:29], v[28:29], v[54:55] op_sel_hi:[1,0]
	v_pk_mul_f32 v[26:27], v[26:27], v[54:55] op_sel_hi:[1,0]
	v_pk_mul_f32 v[4:5], v[4:5], v[54:55] op_sel_hi:[1,0]
	v_pk_mul_f32 v[2:3], v[2:3], v[54:55] op_sel_hi:[1,0]
	v_pk_mul_f32 v[8:9], v[8:9], v[54:55] op_sel_hi:[1,0]
	v_pk_mul_f32 v[6:7], v[6:7], v[54:55] op_sel_hi:[1,0]
	v_mov_b32_e32 v75, v53
.LBB0_216:
	v_sub_f32_e32 v18, v18, v75
	v_exp_f32_e32 v53, v18
	v_sub_f32_e32 v18, v19, v75
	v_exp_f32_e32 v19, v18
	v_sub_f32_e32 v18, v20, v75
	v_exp_f32_e32 v55, v18
	v_sub_f32_e32 v18, v21, v75
	v_exp_f32_e32 v21, v18
	v_sub_f32_e32 v18, v46, v74
	v_exp_f32_e32 v52, v18
	v_sub_f32_e32 v18, v47, v74
	v_sub_f32_e32 v42, v42, v74
	v_exp_f32_e32 v18, v18
	v_sub_f32_e32 v20, v48, v74
	v_exp_f32_e32 v56, v42
	v_sub_f32_e32 v42, v43, v74
	v_exp_f32_e32 v54, v20
	v_sub_f32_e32 v20, v49, v74
	v_exp_f32_e32 v58, v42
	v_sub_f32_e32 v42, v44, v74
	v_sub_f32_e32 v10, v10, v75
	v_exp_f32_e32 v20, v20
	v_exp_f32_e32 v60, v42
	v_sub_f32_e32 v42, v45, v74
	v_exp_f32_e32 v57, v10
	v_sub_f32_e32 v10, v11, v75
	v_exp_f32_e32 v62, v42
	v_pk_add_f32 v[42:43], v[52:53], 0 op_sel_hi:[1,0]
	v_exp_f32_e32 v59, v10
	v_sub_f32_e32 v10, v12, v75
	v_pk_add_f32 v[42:43], v[18:19], v[42:43]
	v_exp_f32_e32 v61, v10
	v_sub_f32_e32 v10, v13, v75
	v_pk_add_f32 v[42:43], v[54:55], v[42:43]
	v_exp_f32_e32 v63, v10
	v_pk_add_f32 v[42:43], v[20:21], v[42:43]
	v_pk_add_f32 v[42:43], v[56:57], v[42:43]
	v_pk_add_f32 v[42:43], v[58:59], v[42:43]
	v_cvt_pk_bf16_f32 v10, v53, v19
	v_pk_add_f32 v[42:43], v[60:61], v[42:43]
	v_cvt_pk_bf16_f32 v11, v55, v21
	v_pk_add_f32 v[42:43], v[62:63], v[42:43]
	v_cvt_pk_bf16_f32 v12, v57, v59
	v_pk_add_f32 v[76:77], v[50:51], v[42:43]
	v_cvt_pk_bf16_f32 v13, v61, v63
	v_cvt_pk_bf16_f32 v18, v52, v18
	v_cvt_pk_bf16_f32 v19, v54, v20
	s_waitcnt lgkmcnt(0)
	v_cvt_pk_bf16_f32 v20, v56, v58
	v_cvt_pk_bf16_f32 v21, v60, v62
	v_mfma_f32_16x16x32_bf16 v[58:61], v[176:179], v[10:13], v[38:41]
	v_mfma_f32_16x16x32_bf16 v[66:69], v[180:183], v[10:13], v[34:37]
	v_mfma_f32_16x16x32_bf16 v[42:45], v[176:179], v[18:21], v[30:33]
	v_mfma_f32_16x16x32_bf16 v[46:49], v[180:183], v[18:21], v[26:29]
	v_mfma_f32_16x16x32_bf16 v[50:53], v[236:239], v[10:13], v[22:25]
	v_mfma_f32_16x16x32_bf16 v[2:5], v[236:239], v[18:21], v[2:5]
	v_mfma_f32_16x16x32_bf16 v[54:57], v[244:247], v[10:13], v[14:17]
	v_mfma_f32_16x16x32_bf16 v[6:9], v[244:247], v[18:21], v[6:9]
	v_mov_b32_e32 v0, v75
	v_mov_b32_e32 v129, v74
